# merge: prefetch loads in MFMA gaps, sigmoid spread over the P-GEMM clusters, default next-call addresses moved off the G-loop common path
# baseline (speedup 1.0000x reference)
; template <int BN>
; DI void gemm_main(f32x16 (&acc)[2][BN / 64], const GDesc& cur, const GDesc& nxt, GRegs<BN>& R, bool preloaded, char* smem) {
;     ...
;   for (int k0 = 0; k0 < K; k0 += 128) {
;     __syncthreads();
;     GM_STORE(R.ra0, R.rb0)
;     __syncthreads();
;     if (k0 + 128 < K) GM_LOAD(R.ra0, R.rb0, ap, wp, lda, ldw, k0 + 128)
;     else if (nxt.valid) GM_LOAD(R.ra0, R.rb0, apn, wpn, nxt.lda, nxt.ldw, 0)
;     GM_COMPUTE()
;     __syncthreads();
;     GM_STORE(R.ra1, R.rb1)
;     __syncthreads();
;     if (k0 + 192 < K) GM_LOAD(R.ra1, R.rb1, ap, wp, lda, ldw, k0 + 192)
;     else if (nxt.valid) GM_LOAD(R.ra1, R.rb1, apn, wpn, nxt.lda, nxt.ldw, 64)
;     GM_COMPUTE()
.LBB0_97:
	s_cmpk_gt_u32 s4, 0x37f
	s_cselect_b64 s[22:23], -1, 0
	s_barrier
	s_waitcnt vmcnt(7)
	ds_write_b128 v116, v[100:103]
	s_waitcnt vmcnt(9)
	ds_write_b128 v116, v[104:107] offset:4608
	s_waitcnt vmcnt(7)
	ds_write_b128 v116, v[92:95] offset:9216
	s_waitcnt vmcnt(5)
	ds_write_b128 v116, v[88:91] offset:13824
	s_waitcnt vmcnt(3)
	ds_write_b128 v116, v[96:99] offset:18432
	s_waitcnt vmcnt(1)
	ds_write_b128 v116, v[108:111] offset:23040
	s_and_b64 vcc, exec, s[22:23]
	v_lshl_add_u64 v[114:115], v[24:25], 0, v[168:169]
	s_waitcnt lgkmcnt(0)
	s_barrier
	s_cbranch_vccnz .Lmg_def0
	s_mov_b64 s[30:31], 0x4110200
	v_lshl_add_u64 v[100:101], v[114:115], 0, s[30:31]
	s_mov_b64 s[30:31], 0x4140200
	v_lshl_add_u64 v[90:91], v[114:115], 0, s[30:31]
	s_mov_b64 s[30:31], 0x4130200
	v_lshl_add_u64 v[92:93], v[114:115], 0, s[30:31]
	s_mov_b64 s[30:31], 0x4120200
	v_lshl_add_u64 v[88:89], v[112:113], 0, v[168:169]
	v_lshl_add_u64 v[108:109], v[30:31], 0, v[168:169]
	v_lshl_add_u64 v[102:103], v[114:115], 0, s[30:31]
	s_mov_b64 s[30:31], s[34:35]
.LBB0_99:
	s_setprio 1
	ds_read_b128 v[120:123], v117 offset:4608
	ds_read_b128 v[156:159], v117
	ds_read_b128 v[160:163], v117 offset:32
	ds_read_b128 v[164:167], v118 offset:18432
	ds_read_b128 v[174:177], v118 offset:18464
	s_waitcnt lgkmcnt(1)
	v_mfma_f32_32x32x16_bf16 v[48:63], v[156:159], v[164:167], v[48:63]
	ds_read_b128 v[156:159], v117 offset:4672
	global_load_dwordx4 v[96:99], v[88:89], off
	v_mfma_f32_32x32x16_bf16 v[32:47], v[120:123], v[164:167], v[32:47]
	ds_read_b128 v[120:123], v117 offset:4640
	global_load_dwordx4 v[104:107], v[102:103], off
	s_waitcnt lgkmcnt(2)
	v_mfma_f32_32x32x16_bf16 v[48:63], v[160:163], v[174:177], v[48:63]
	ds_read_b128 v[160:163], v118 offset:18496
	global_load_dwordx4 v[88:91], v[90:91], off
	s_waitcnt lgkmcnt(1)
	v_mfma_f32_32x32x16_bf16 v[32:47], v[120:123], v[174:177], v[32:47]
	ds_read_b128 v[120:123], v117 offset:64
	global_load_dwordx4 v[92:95], v[92:93], off
	s_waitcnt lgkmcnt(0)
	v_mfma_f32_32x32x16_bf16 v[48:63], v[120:123], v[160:163], v[48:63]
	global_load_dwordx4 v[100:103], v[100:101], off
	v_mfma_f32_32x32x16_bf16 v[32:47], v[156:159], v[160:163], v[32:47]
	ds_read_b128 v[160:163], v118 offset:18528
	ds_read_b128 v[156:159], v117 offset:4704
	global_load_dwordx4 v[108:111], v[108:109], off
	s_waitcnt lgkmcnt(0)
	v_mfma_f32_32x32x16_bf16 v[32:47], v[156:159], v[160:163], v[32:47]
	ds_read_b128 v[120:123], v117 offset:96
	s_waitcnt lgkmcnt(0)
	v_mfma_f32_32x32x16_bf16 v[48:63], v[120:123], v[160:163], v[48:63]
	s_setprio 0
	s_barrier
	ds_write_b128 v116, v[76:79]
	ds_write_b128 v116, v[68:71] offset:9216
	ds_write_b128 v116, v[64:67] offset:13824
	s_waitcnt vmcnt(6)
	ds_write_b128 v116, v[84:87] offset:23040
	s_cmpk_gt_u32 s4, 0x33f
	ds_write_b128 v116, v[80:83] offset:4608
	ds_write_b128 v116, v[72:75] offset:18432
	s_waitcnt lgkmcnt(0)
	s_barrier
	s_cbranch_scc1 .Lmg_def1
	s_mov_b64 s[30:31], 0x4110280
	v_lshl_add_u64 v[76:77], v[114:115], 0, s[30:31]
	s_mov_b64 s[30:31], 0x4140280
	v_lshl_add_u64 v[66:67], v[114:115], 0, s[30:31]
	s_mov_b64 s[30:31], 0x4130280
	v_lshl_add_u64 v[68:69], v[114:115], 0, s[30:31]
	s_mov_b64 s[30:31], 0x4120280
	v_lshl_add_u64 v[64:65], v[28:29], 0, v[168:169]
	v_lshl_add_u64 v[84:85], v[26:27], 0, v[168:169]
	v_lshl_add_u64 v[78:79], v[114:115], 0, s[30:31]
	s_mov_b64 s[30:31], s[34:35]
	s_branch .LBB0_96
.Lmg_def0:
	v_mov_b64_e32 v[100:101], v[0:1]
	v_mov_b64_e32 v[102:103], v[8:9]
	v_mov_b64_e32 v[92:93], v[10:11]
	v_mov_b64_e32 v[90:91], v[12:13]
	v_mov_b64_e32 v[88:89], v[2:3]
	v_mov_b64_e32 v[108:109], v[14:15]
	s_branch .LBB0_99
.Lmg_def1:
	v_mov_b64_e32 v[76:77], v[4:5]
	v_mov_b64_e32 v[78:79], v[16:17]
	v_mov_b64_e32 v[68:69], v[18:19]
	v_mov_b64_e32 v[66:67], v[20:21]
	v_mov_b64_e32 v[64:65], v[6:7]
	v_mov_b64_e32 v[84:85], v[22:23]
	s_branch .LBB0_96
